# filter_phase inner product: even/odd k accumulated in packed pairs (no register shuffles, f32 sums reassociated), weight loads prefetched 3 iterations ahead; attention mask selects issued in pairs wit
# speedup vs baseline: 1.0070x; 1.0017x over previous
; __device__ void attn_phase(unsigned char* smem, const Params& p, int chunk) {
;     ...
;         const int qi = qs * 16 + r16; const int qp = n * 64 + qi; const size_t qtok = brow + ((size_t)qp << dsh) + res;
;         int lo = -64, hi = 64;
;         if (n == 0) lo = max(-64, -qi);
;         if (n == nbk - 1) hi = min(64, 63 - qi);
;         const int cbase = 4 * g4 - r16 - 64;
;         const unsigned ub = (unsigned)(cbase - lo), rng = (unsigned)(hi - lo);
;         const float* bl = bs + (cbase + 64);
;         f32x4 s[10];
; #pragma unroll
;         for (int kt = 0; kt < 9; ++kt) { s[kt] = (f32x4){0.f, 0.f, 0.f, 0.f};
; #pragma unroll
;             for (int ks = 0; ks < 2; ++ks) { const bf16x8 kfr = *(const bf16x8*)(Ks + (hoff + qs * 16 + kt * 16 + r16) * KST + ks * 32 + g4 * 8); s[kt] = __builtin_amdgcn_mfma_f32_16x16x32_bf16(kfr, qf[ks], s[kt], 0, 0, 0); } }
.LBB0_76:
	ds_read_b128 v[56:59], v99
	ds_read_b128 v[60:63], v99 offset:64
	ds_read_b128 v[64:67], v99 offset:2304
	ds_read_b128 v[68:71], v99 offset:2368
	ds_read_b128 v[72:75], v99 offset:4608
	s_mul_hi_i32 s31, s24, 0x2aaaaaab
	s_waitcnt lgkmcnt(4)
	v_mfma_f32_16x16x32_bf16 v[56:59], v[56:59], v[52:55], 0
	s_lshr_b32 s34, s31, 31
	s_lshr_b32 s31, s31, 10
	s_add_i32 s31, s31, s34
	s_waitcnt lgkmcnt(3)
	v_mfma_f32_16x16x32_bf16 v[84:87], v[60:63], v[48:51], v[56:59]
	ds_read_b128 v[60:63], v99 offset:6912
	s_mulk_i32 s31, 0x1800
	s_sub_i32 s34, s24, s31
	ds_read_b128 v[56:59], v99 offset:4672
	s_waitcnt lgkmcnt(4)
	v_mfma_f32_16x16x32_bf16 v[64:67], v[64:67], v[52:55], 0
	s_bfe_i32 s35, s34, 0x100004
	s_mulk_i32 s35, 0x2aab
	s_lshr_b32 s36, s35, 31
	s_waitcnt lgkmcnt(3)
	v_mfma_f32_16x16x32_bf16 v[80:83], v[68:71], v[48:51], v[64:67]
	ds_read_b128 v[68:71], v99 offset:6976
	s_lshr_b32 s35, s35, 18
	s_lshl_b32 s24, s34, 1
	s_waitcnt lgkmcnt(3)
	v_mfma_f32_16x16x32_bf16 v[64:67], v[72:75], v[52:55], 0
	ds_read_b128 v[114:117], v99 offset:11584
	s_add_i32 s35, s35, s36
	s_and_b32 s31, s24, 30
	s_waitcnt lgkmcnt(2)
	v_mfma_f32_16x16x32_bf16 v[76:79], v[56:59], v[48:51], v[64:67]
	ds_read_b128 v[56:59], v99 offset:9216
	s_lshr_b32 s24, s34, 4
	s_mul_i32 s35, s35, 24
	ds_read_b128 v[64:67], v99 offset:9280
	v_mfma_f32_16x16x32_bf16 v[60:63], v[60:63], v[52:55], 0
	ds_read_b128 v[118:121], v99 offset:13888
	s_sub_i32 s24, s24, s35
	s_sext_i32_i16 s52, s24
	s_waitcnt lgkmcnt(2)
	v_mfma_f32_16x16x32_bf16 v[56:59], v[56:59], v[52:55], 0
	ds_read_b128 v[122:125], v99 offset:16192
	s_ashr_i32 s24, s52, 2
	s_and_b32 s24, s24, -2
	v_mfma_f32_16x16x32_bf16 v[72:75], v[68:71], v[48:51], v[60:63]
	s_lshr_b32 s35, 32, s24
	s_add_i32 s35, s35, -1
	s_and_b32 s36, s35, s31
	ds_read_b128 v[60:63], v99 offset:11520
	s_waitcnt lgkmcnt(3)
	v_mfma_f32_16x16x32_bf16 v[68:71], v[64:67], v[48:51], v[56:59]
	ds_read_b128 v[126:129], v99 offset:18496
	v_add_u32_e32 v101, s36, v103
	v_not_b32_e32 v113, 63
	ds_read_b128 v[56:59], v99 offset:13824
	s_waitcnt lgkmcnt(2)
	v_mfma_f32_16x16x32_bf16 v[60:63], v[60:63], v[52:55], 0
	v_cmp_eq_u32_e32 vcc, 0, v101
	s_waitcnt lgkmcnt(0)
	v_mfma_f32_16x16x32_bf16 v[56:59], v[56:59], v[52:55], 0
	v_cndmask_b32_e32 v113, v113, v107, vcc
	v_cmp_eq_u32_e32 vcc, s35, v101
	v_mfma_f32_16x16x32_bf16 v[64:67], v[114:117], v[48:51], v[60:63]
	ds_read_b128 v[114:117], v99 offset:16128
	v_mfma_f32_16x16x32_bf16 v[60:63], v[118:121], v[48:51], v[56:59]
	ds_read_b128 v[118:121], v99 offset:18432
	s_waitcnt lgkmcnt(1)
	v_mfma_f32_16x16x32_bf16 v[56:59], v[114:117], v[52:55], 0
	v_cndmask_b32_e32 v114, 64, v108, vcc
	v_sub_u32_e32 v115, v109, v113
	v_sub_u32_e32 v116, v114, v113
	s_waitcnt lgkmcnt(0)
	v_mfma_f32_16x16x32_bf16 v[52:55], v[118:121], v[52:55], 0
	ds_read_b32 v142, v110
	ds_read_b32 v143, v110 offset:4
	ds_read_b32 v144, v110 offset:8
	ds_read_b32 v145, v110 offset:12
	ds_read_b32 v146, v110 offset:64
	ds_read_b32 v147, v110 offset:68
	ds_read_b32 v148, v110 offset:72
	ds_read_b32 v149, v110 offset:76
	ds_read_b32 v150, v110 offset:128
	ds_read_b32 v151, v110 offset:132
	ds_read_b32 v152, v110 offset:136
	ds_read_b32 v153, v110 offset:140
	ds_read_b32 v154, v110 offset:192
	ds_read_b32 v155, v110 offset:196
	ds_read_b32 v156, v110 offset:200
	ds_read_b32 v157, v110 offset:204
	ds_read_b32 v158, v110 offset:256
	ds_read_b32 v159, v110 offset:260
	ds_read_b32 v160, v110 offset:264
	ds_read_b32 v161, v110 offset:268
	ds_read_b32 v162, v110 offset:320
	ds_read_b32 v163, v110 offset:324
	ds_read_b32 v164, v110 offset:328
	ds_read_b32 v165, v110 offset:332
	ds_read_b32 v166, v110 offset:384
	ds_read_b32 v167, v110 offset:388
	ds_read_b32 v168, v110 offset:392
	ds_read_b32 v169, v110 offset:396
	ds_read_b32 v170, v110 offset:448
	ds_read_b32 v171, v110 offset:452
	ds_read_b32 v172, v110 offset:456
	ds_read_b32 v173, v110 offset:460
	ds_read_b32 v174, v110 offset:512
	ds_read_b32 v175, v110 offset:516
	ds_read_b32 v176, v110 offset:520
	ds_read_b32 v177, v110 offset:524
	v_mfma_f32_16x16x32_bf16 v[56:59], v[122:125], v[48:51], v[56:59]
	v_mfma_f32_16x16x32_bf16 v[48:51], v[126:129], v[48:51], v[52:55]
	v_mov_b32_e32 v179, 0xf149f2ca
	s_waitcnt lgkmcnt(0)
; __device__ void attn_phase(unsigned char* smem, const Params& p, int chunk) {
;     ...
; #pragma unroll
;         for (int kt = 0; kt < 9; ++kt)
; #pragma unroll
;             for (int i = 0; i < 4; ++i) { const bool valid = (ub + (unsigned)(16 * kt + i)) <= rng;
;                 const float v = valid ? __builtin_fmaf(s[kt][i], 0.125f * 1.4426950408889634f, bl[16 * kt + i]) : -1e30f; s[kt][i] = v; mx = fmaxf(mx, v); }
;         mx = fmaxf(mx, __shfl_xor(mx, 16)); mx = fmaxf(mx, __shfl_xor(mx, 32));
	v_add_u32_e32 v180, 1, v115
	v_cmp_le_u32_e32 vcc, v115, v116
	v_cmp_le_u32_e64 s[98:99], v180, v116
	v_fmac_f32_e32 v142, 0x3e38aa3b, v84
	v_fmac_f32_e32 v143, 0x3e38aa3b, v85
	v_cndmask_b32_e32 v114, v179, v142, vcc
	v_cndmask_b32_e64 v113, v179, v143, s[98:99]
	v_add_u32_e32 v178, 2, v115
	v_add_u32_e32 v180, 3, v115
	v_cmp_le_u32_e32 vcc, v178, v116
	v_cmp_le_u32_e64 s[98:99], v180, v116
	v_fmac_f32_e32 v144, 0x3e38aa3b, v86
	v_fmac_f32_e32 v145, 0x3e38aa3b, v87
	v_cndmask_b32_e32 v85, v179, v144, vcc
	v_cndmask_b32_e64 v84, v179, v145, s[98:99]
	v_add_u32_e32 v178, 16, v115
	v_add_u32_e32 v180, 17, v115
	v_cmp_le_u32_e32 vcc, v178, v116
	v_cmp_le_u32_e64 s[98:99], v180, v116
	v_fmac_f32_e32 v146, 0x3e38aa3b, v80
	v_fmac_f32_e32 v147, 0x3e38aa3b, v81
	v_cndmask_b32_e32 v87, v179, v146, vcc
	v_cndmask_b32_e64 v86, v179, v147, s[98:99]
	v_add_u32_e32 v178, 18, v115
	v_add_u32_e32 v180, 19, v115
	v_cmp_le_u32_e32 vcc, v178, v116
	v_cmp_le_u32_e64 s[98:99], v180, v116
	v_fmac_f32_e32 v148, 0x3e38aa3b, v82
	v_fmac_f32_e32 v149, 0x3e38aa3b, v83
	v_cndmask_b32_e32 v81, v179, v148, vcc
	v_cndmask_b32_e64 v80, v179, v149, s[98:99]
	v_add_u32_e32 v178, 32, v115
	v_add_u32_e32 v180, 33, v115
	v_cmp_le_u32_e32 vcc, v178, v116
	v_cmp_le_u32_e64 s[98:99], v180, v116
	v_fmac_f32_e32 v150, 0x3e38aa3b, v76
	v_fmac_f32_e32 v151, 0x3e38aa3b, v77
	v_cndmask_b32_e32 v83, v179, v150, vcc
	v_cndmask_b32_e64 v82, v179, v151, s[98:99]
	v_add_u32_e32 v178, 34, v115
	v_add_u32_e32 v180, 35, v115
	v_cmp_le_u32_e32 vcc, v178, v116
	v_cmp_le_u32_e64 s[98:99], v180, v116
	v_fmac_f32_e32 v152, 0x3e38aa3b, v78
	v_fmac_f32_e32 v153, 0x3e38aa3b, v79
	v_cndmask_b32_e32 v77, v179, v152, vcc
	v_cndmask_b32_e64 v76, v179, v153, s[98:99]
	v_add_u32_e32 v178, 48, v115
	v_add_u32_e32 v180, 49, v115
	v_cmp_le_u32_e32 vcc, v178, v116
	v_cmp_le_u32_e64 s[98:99], v180, v116
	v_fmac_f32_e32 v154, 0x3e38aa3b, v72
	v_fmac_f32_e32 v155, 0x3e38aa3b, v73
	v_cndmask_b32_e32 v79, v179, v154, vcc
	v_cndmask_b32_e64 v78, v179, v155, s[98:99]
	v_add_u32_e32 v178, 50, v115
	v_add_u32_e32 v180, 51, v115
	v_cmp_le_u32_e32 vcc, v178, v116
	v_cmp_le_u32_e64 s[98:99], v180, v116
	v_fmac_f32_e32 v156, 0x3e38aa3b, v74
	v_fmac_f32_e32 v157, 0x3e38aa3b, v75
	v_cndmask_b32_e32 v73, v179, v156, vcc
	v_cndmask_b32_e64 v72, v179, v157, s[98:99]
	v_add_u32_e32 v178, 64, v115
	v_add_u32_e32 v180, 0x41, v115
	v_cmp_le_u32_e32 vcc, v178, v116
	v_cmp_le_u32_e64 s[98:99], v180, v116
	v_fmac_f32_e32 v158, 0x3e38aa3b, v68
	v_fmac_f32_e32 v159, 0x3e38aa3b, v69
	v_cndmask_b32_e32 v75, v179, v158, vcc
	v_cndmask_b32_e64 v74, v179, v159, s[98:99]
	v_add_u32_e32 v178, 0x42, v115
	v_add_u32_e32 v180, 0x43, v115
	v_cmp_le_u32_e32 vcc, v178, v116
	v_cmp_le_u32_e64 s[98:99], v180, v116
	v_fmac_f32_e32 v160, 0x3e38aa3b, v70
	v_fmac_f32_e32 v161, 0x3e38aa3b, v71
	v_cndmask_b32_e32 v69, v179, v160, vcc
	v_cndmask_b32_e64 v68, v179, v161, s[98:99]
	v_add_u32_e32 v178, 0x50, v115
	v_add_u32_e32 v180, 0x51, v115
	v_cmp_le_u32_e32 vcc, v178, v116
	v_cmp_le_u32_e64 s[98:99], v180, v116
	v_fmac_f32_e32 v162, 0x3e38aa3b, v64
	v_fmac_f32_e32 v163, 0x3e38aa3b, v65
	v_cndmask_b32_e32 v71, v179, v162, vcc
	v_cndmask_b32_e64 v70, v179, v163, s[98:99]
	v_add_u32_e32 v178, 0x52, v115
	v_add_u32_e32 v180, 0x53, v115
	v_cmp_le_u32_e32 vcc, v178, v116
	v_cmp_le_u32_e64 s[98:99], v180, v116
	v_fmac_f32_e32 v164, 0x3e38aa3b, v66
	v_fmac_f32_e32 v165, 0x3e38aa3b, v67
	v_cndmask_b32_e32 v118, v179, v164, vcc
	v_cndmask_b32_e64 v117, v179, v165, s[98:99]
	v_add_u32_e32 v178, 0x60, v115
	v_add_u32_e32 v180, 0x61, v115
	v_cmp_le_u32_e32 vcc, v178, v116
	v_cmp_le_u32_e64 s[98:99], v180, v116
	v_fmac_f32_e32 v166, 0x3e38aa3b, v60
	v_fmac_f32_e32 v167, 0x3e38aa3b, v61
	v_cndmask_b32_e32 v65, v179, v166, vcc
	v_cndmask_b32_e64 v64, v179, v167, s[98:99]
	v_add_u32_e32 v178, 0x62, v115
	v_add_u32_e32 v180, 0x63, v115
	v_cmp_le_u32_e32 vcc, v178, v116
	v_cmp_le_u32_e64 s[98:99], v180, v116
	v_fmac_f32_e32 v168, 0x3e38aa3b, v62
	v_fmac_f32_e32 v169, 0x3e38aa3b, v63
	v_cndmask_b32_e32 v66, v179, v168, vcc
	v_cndmask_b32_e64 v60, v179, v169, s[98:99]
	v_add_u32_e32 v178, 0x70, v115
	v_add_u32_e32 v180, 0x71, v115
	v_cmp_le_u32_e32 vcc, v178, v116
	v_cmp_le_u32_e64 s[98:99], v180, v116
	v_fmac_f32_e32 v170, 0x3e38aa3b, v56
	v_fmac_f32_e32 v171, 0x3e38aa3b, v57
	v_cndmask_b32_e32 v62, v179, v170, vcc
	v_cndmask_b32_e64 v61, v179, v171, s[98:99]
	v_add_u32_e32 v178, 0x72, v115
	v_add_u32_e32 v180, 0x73, v115
	v_cmp_le_u32_e32 vcc, v178, v116
	v_cmp_le_u32_e64 s[98:99], v180, v116
	v_fmac_f32_e32 v172, 0x3e38aa3b, v58
	v_fmac_f32_e32 v173, 0x3e38aa3b, v59
	v_cndmask_b32_e32 v55, v179, v172, vcc
	v_cndmask_b32_e64 v54, v179, v173, s[98:99]
	v_add_u32_e32 v178, 0x80, v115
	v_add_u32_e32 v180, 0x81, v115
	v_cmp_le_u32_e32 vcc, v178, v116
	v_cmp_le_u32_e64 s[98:99], v180, v116
	v_fmac_f32_e32 v174, 0x3e38aa3b, v48
	v_fmac_f32_e32 v175, 0x3e38aa3b, v49
	v_cndmask_b32_e32 v56, v179, v174, vcc
	v_cndmask_b32_e64 v52, v179, v175, s[98:99]
	v_add_u32_e32 v178, 0x82, v115
	v_add_u32_e32 v180, 0x83, v115
	v_cmp_le_u32_e32 vcc, v178, v116
	v_cmp_le_u32_e64 s[98:99], v180, v116
	v_fmac_f32_e32 v176, 0x3e38aa3b, v50
	v_fmac_f32_e32 v177, 0x3e38aa3b, v51
	v_cndmask_b32_e32 v53, v179, v176, vcc
	v_cndmask_b32_e64 v49, v179, v177, s[98:99]
	s_mov_b32 s35, 0xf149f2ca
	v_max3_f32 v48, v114, s35, v113
	v_max3_f32 v48, v48, v85, v84
	v_max3_f32 v48, v48, v87, v86
	v_max3_f32 v48, v48, v81, v80
	v_max3_f32 v48, v48, v83, v82
	v_max3_f32 v48, v48, v77, v76
	v_max3_f32 v48, v48, v79, v78
	v_max3_f32 v48, v48, v73, v72
	v_max3_f32 v48, v48, v75, v74
	v_max3_f32 v48, v48, v69, v68
	v_max3_f32 v48, v48, v71, v70
	v_max3_f32 v48, v48, v118, v117
	v_max3_f32 v48, v48, v65, v64
	v_max3_f32 v48, v48, v66, v60
	v_max3_f32 v48, v48, v62, v61
	v_max3_f32 v48, v48, v55, v54
	v_max3_f32 v48, v48, v56, v52
	v_and_b32_e32 v51, 64, v243
	v_max3_f32 v50, v48, v53, v49
	v_xor_b32_e32 v48, 16, v243
	v_add_u32_e32 v51, 64, v51
	v_cmp_lt_i32_e32 vcc, v48, v51
	s_mulk_i32 s34, 0x2aab
	s_lshr_b32 s35, s34, 31
	v_cndmask_b32_e32 v48, v243, v48, vcc
	v_lshlrev_b32_e32 v48, 2, v48
	ds_bpermute_b32 v57, v48, v50
	s_ashr_i32 s34, s34, 22
	s_add_i32 s34, s34, s35
	s_sub_i32 s35, 5, s24
	s_bfe_i64 s[58:59], s[34:35], 0x100000
	s_waitcnt lgkmcnt(0)
; #define LAS __attribute__((address_space(3)))
; __device__ __forceinline__ unsigned cvt_pk_bf16(float lo, float hi) { const f32x2_t v = {lo, hi}; const bf16x2_t b = __builtin_convertvector(v, bf16x2_t); return __builtin_bit_cast(unsigned, b); }
; __device__ void attn_phase(unsigned char* smem, const Params& p, int chunk) {
;     ...
;         mx = fmaxf(mx, __shfl_xor(mx, 16)); mx = fmaxf(mx, __shfl_xor(mx, 32));
;         float den = 0.f;
; #pragma unroll
;         for (int kt = 0; kt < 9; ++kt)
; #pragma unroll
;             for (int i = 0; i < 4; ++i) { const float e = __builtin_amdgcn_exp2f(s[kt][i] - mx); s[kt][i] = e; den += e; }
;         den += __shfl_xor(den, 16); den += __shfl_xor(den, 32);
;         f32x4 o[4];
; #pragma unroll
;         for (int et = 0; et < 4; ++et) o[et] = (f32x4){0.f, 0.f, 0.f, 0.f};
;         const bf16_t* vbase = Vs + (hoff + qs * 16 + 4 * g4 + (r16 >> 2)) * VSR + 4 * (r16 & 3);
; #pragma unroll
;         for (int cc = 0; cc < 5; ++cc) {
;             union { u32x4 u; bf16x8 v; } pf; pf.u.x = cvt_pk_bf16(s[2 * cc][0], s[2 * cc][1]); pf.u.y = cvt_pk_bf16(s[2 * cc][2], s[2 * cc][3]);
;             pf.u.z = cvt_pk_bf16(s[2 * cc + 1][0], s[2 * cc + 1][1]); pf.u.w = cvt_pk_bf16(s[2 * cc + 1][2], s[2 * cc + 1][3]);
; #pragma unroll
;             for (int et = 0; et < 4; ++et) { const bf16_t* vp = vbase + (cc * 32) * VSR + et * 16;
;                 const s16x4 v0 = __builtin_amdgcn_ds_read_tr16_b64_v4i16((LAS s16x4*)(LAS unsigned char*)vp), v1 = __builtin_amdgcn_ds_read_tr16_b64_v4i16((LAS s16x4*)(LAS unsigned char*)(vp + 16 * VSR));
;                 const bf16x8 vf = {v0[0], v0[1], v0[2], v0[3], v1[0], v1[1], v1[2], v1[3]};
;                 o[et] = __builtin_amdgcn_mfma_f32_16x16x32_bf16(vf, pf.v, o[et], 0, 0, 0); } }
	v_max_f32_e32 v57, v57, v57
	v_max_f32_e32 v50, v50, v57
	v_xor_b32_e32 v57, 32, v243
	v_cmp_lt_i32_e32 vcc, v57, v51
	s_lshr_b32 s31, s31, s35
	s_lshl_b64 s[34:35], s[58:59], 11
	v_cndmask_b32_e32 v51, v243, v57, vcc
	v_lshlrev_b32_e32 v51, 2, v51
	ds_bpermute_b32 v57, v51, v50
	s_or_b32 s34, s34, s31
	s_waitcnt lgkmcnt(0)
	v_max_f32_e32 v57, v57, v57
	v_max_f32_e32 v50, v50, v57
	v_sub_f32_e32 v57, v114, v50
	v_exp_f32_e32 v57, v57
	v_sub_f32_e32 v58, v113, v50
	v_exp_f32_e32 v58, v58
	v_sub_f32_e32 v59, v85, v50
	v_exp_f32_e32 v59, v59
	v_sub_f32_e32 v63, v84, v50
	v_exp_f32_e32 v63, v63
	v_sub_f32_e32 v84, v87, v50
	v_add_f32_e32 v67, 0, v57
	v_exp_f32_e32 v84, v84
	v_sub_f32_e32 v85, v86, v50
	v_add_f32_e32 v67, v58, v67
	v_exp_f32_e32 v85, v85
	v_sub_f32_e32 v81, v81, v50
	v_add_f32_e32 v67, v59, v67
	v_exp_f32_e32 v81, v81
	v_sub_f32_e32 v80, v80, v50
	v_add_f32_e32 v67, v63, v67
	v_exp_f32_e32 v80, v80
	v_sub_f32_e32 v83, v83, v50
	v_add_f32_e32 v67, v84, v67
	v_exp_f32_e32 v113, v83
	v_sub_f32_e32 v82, v82, v50
	v_add_f32_e32 v67, v85, v67
	v_exp_f32_e32 v114, v82
	v_sub_f32_e32 v77, v77, v50
	v_add_f32_e32 v67, v81, v67
	v_exp_f32_e32 v115, v77
	v_sub_f32_e32 v76, v76, v50
	v_add_f32_e32 v67, v80, v67
	v_exp_f32_e32 v116, v76
	v_sub_f32_e32 v76, v79, v50
	v_add_f32_e32 v67, v113, v67
	v_exp_f32_e32 v119, v76
	v_sub_f32_e32 v76, v78, v50
	v_add_f32_e32 v67, v114, v67
	v_exp_f32_e32 v120, v76
	v_sub_f32_e32 v73, v73, v50
	v_add_f32_e32 v67, v115, v67
	v_exp_f32_e32 v121, v73
	v_sub_f32_e32 v72, v72, v50
	v_add_f32_e32 v67, v116, v67
	v_exp_f32_e32 v122, v72
	v_sub_f32_e32 v72, v75, v50
	v_add_f32_e32 v67, v119, v67
	v_exp_f32_e32 v126, v72
	v_sub_f32_e32 v72, v74, v50
	v_add_f32_e32 v67, v120, v67
	v_exp_f32_e32 v127, v72
	v_sub_f32_e32 v69, v69, v50
	v_add_f32_e32 v67, v121, v67
	v_exp_f32_e32 v128, v69
	v_sub_f32_e32 v68, v68, v50
	v_add_f32_e32 v67, v122, v67
	v_exp_f32_e32 v129, v68
	v_sub_f32_e32 v68, v71, v50
	v_add_f32_e32 v67, v126, v67
	v_exp_f32_e32 v130, v68
	v_sub_f32_e32 v68, v70, v50
	v_add_f32_e32 v67, v127, v67
	v_exp_f32_e32 v131, v68
	v_sub_f32_e32 v68, v118, v50
	v_add_f32_e32 v67, v128, v67
	v_exp_f32_e32 v132, v68
	v_sub_f32_e32 v68, v117, v50
	v_add_f32_e32 v67, v129, v67
	v_exp_f32_e32 v133, v68
	v_cvt_pk_bf16_f32 v68, v57, v58
	ds_read_b64_tr_b16 v[74:75], v111 offset:41472
	ds_read_b64_tr_b16 v[72:73], v111 offset:39168
	v_cvt_pk_bf16_f32 v70, v84, v85
	v_cvt_pk_bf16_f32 v71, v81, v80
	ds_read_b64_tr_b16 v[78:79], v111 offset:41504
	ds_read_b64_tr_b16 v[76:77], v111 offset:39200
	ds_read_b64_tr_b16 v[80:81], v111 offset:39232
	ds_read_b64_tr_b16 v[84:85], v111 offset:39264
	ds_read_b64_tr_b16 v[82:83], v111 offset:41536
	ds_read_b64_tr_b16 v[86:87], v111 offset:41568
	v_sub_f32_e32 v57, v65, v50
	v_add_f32_e32 v67, v130, v67
	v_exp_f32_e32 v134, v57
	v_add_f32_e32 v67, v131, v67
	v_add_f32_e32 v67, v132, v67
	v_sub_f32_e32 v57, v64, v50
	v_add_f32_e32 v117, v133, v67
	v_cvt_pk_bf16_f32 v69, v59, v63
	v_exp_f32_e32 v135, v57
	v_sub_f32_e32 v57, v66, v50
	s_waitcnt lgkmcnt(6)
	v_mfma_f32_16x16x32_bf16 v[72:75], v[72:75], v[68:71], 0
	v_exp_f32_e32 v136, v57
	v_add_f32_e32 v57, v134, v117
	v_sub_f32_e32 v58, v60, v50
	s_waitcnt lgkmcnt(4)
	v_mfma_f32_16x16x32_bf16 v[76:79], v[76:79], v[68:71], 0
	v_add_f32_e32 v57, v135, v57
	v_sub_f32_e32 v55, v55, v50
	v_add_f32_e32 v57, v136, v57
	s_waitcnt lgkmcnt(1)
	v_mfma_f32_16x16x32_bf16 v[64:67], v[80:83], v[68:71], 0
	v_cvt_pk_bf16_f32 v80, v113, v114
	v_cvt_pk_bf16_f32 v81, v115, v116
	v_cvt_pk_bf16_f32 v82, v119, v120
	s_waitcnt lgkmcnt(0)
	v_mfma_f32_16x16x32_bf16 v[68:71], v[84:87], v[68:71], 0
	ds_read_b64_tr_b16 v[84:85], v111 offset:43776
	ds_read_b64_tr_b16 v[86:87], v111 offset:46080
	v_cvt_pk_bf16_f32 v83, v121, v122
	ds_read_b64_tr_b16 v[116:117], v111 offset:46112
	ds_read_b64_tr_b16 v[114:115], v111 offset:43808
	ds_read_b64_tr_b16 v[118:119], v111 offset:43840
	ds_read_b64_tr_b16 v[122:123], v111 offset:43872
	ds_read_b64_tr_b16 v[120:121], v111 offset:46144
	ds_read_b64_tr_b16 v[124:125], v111 offset:46176
	v_exp_f32_e32 v113, v58
	v_sub_f32_e32 v58, v62, v50
	v_exp_f32_e32 v137, v58
	v_sub_f32_e32 v58, v61, v50
	s_waitcnt lgkmcnt(6)
	v_mfma_f32_16x16x32_bf16 v[72:75], v[84:87], v[80:83], v[72:75]
	v_exp_f32_e32 v138, v58
	v_sub_f32_e32 v54, v54, v50
	v_add_f32_e32 v57, v113, v57
	s_waitcnt lgkmcnt(4)
	v_mfma_f32_16x16x32_bf16 v[76:79], v[114:117], v[80:83], v[76:79]
	v_add_f32_e32 v57, v137, v57
	v_add_f32_e32 v139, v138, v57
	v_sub_f32_e32 v52, v52, v50
	s_waitcnt lgkmcnt(1)
	v_mfma_f32_16x16x32_bf16 v[58:61], v[118:121], v[80:83], v[64:67]
	v_sub_f32_e32 v49, v49, v50
	v_exp_f32_e32 v49, v49
	s_waitcnt lgkmcnt(0)
	v_mfma_f32_16x16x32_bf16 v[62:65], v[122:125], v[80:83], v[68:71]
	ds_read_b64_tr_b16 v[80:81], v111 offset:48384
	ds_read_b64_tr_b16 v[82:83], v111 offset:50688
	v_cvt_pk_bf16_f32 v66, v126, v127
	v_cvt_pk_bf16_f32 v67, v128, v129
	v_cvt_pk_bf16_f32 v68, v130, v131
	v_cvt_pk_bf16_f32 v69, v132, v133
	ds_read_b64_tr_b16 v[86:87], v111 offset:50720
	ds_read_b64_tr_b16 v[84:85], v111 offset:48416
	ds_read_b64_tr_b16 v[114:115], v111 offset:48448
	ds_read_b64_tr_b16 v[118:119], v111 offset:48480
	ds_read_b64_tr_b16 v[116:117], v111 offset:50752
	ds_read_b64_tr_b16 v[120:121], v111 offset:50784
	s_waitcnt lgkmcnt(6)
; #define LAS __attribute__((address_space(3)))
; __device__ __forceinline__ unsigned cvt_pk_bf16(float lo, float hi) { const f32x2_t v = {lo, hi}; const bf16x2_t b = __builtin_convertvector(v, bf16x2_t); return __builtin_bit_cast(unsigned, b); }
; __device__ void attn_phase(unsigned char* smem, const Params& p, int chunk) {
;     ...
;         den += __shfl_xor(den, 16); den += __shfl_xor(den, 32);
;         f32x4 o[4];
; #pragma unroll
;         for (int et = 0; et < 4; ++et) o[et] = (f32x4){0.f, 0.f, 0.f, 0.f};
;         const bf16_t* vbase = Vs + (hoff + qs * 16 + 4 * g4 + (r16 >> 2)) * VSR + 4 * (r16 & 3);
; #pragma unroll
;         for (int cc = 0; cc < 5; ++cc) {
;             union { u32x4 u; bf16x8 v; } pf; pf.u.x = cvt_pk_bf16(s[2 * cc][0], s[2 * cc][1]); pf.u.y = cvt_pk_bf16(s[2 * cc][2], s[2 * cc][3]);
;             pf.u.z = cvt_pk_bf16(s[2 * cc + 1][0], s[2 * cc + 1][1]); pf.u.w = cvt_pk_bf16(s[2 * cc + 1][2], s[2 * cc + 1][3]);
; #pragma unroll
;             for (int et = 0; et < 4; ++et) { const bf16_t* vp = vbase + (cc * 32) * VSR + et * 16;
;                 const s16x4 v0 = __builtin_amdgcn_ds_read_tr16_b64_v4i16((LAS s16x4*)(LAS unsigned char*)vp), v1 = __builtin_amdgcn_ds_read_tr16_b64_v4i16((LAS s16x4*)(LAS unsigned char*)(vp + 16 * VSR));
;                 const bf16x8 vf = {v0[0], v0[1], v0[2], v0[3], v1[0], v1[1], v1[2], v1[3]};
;                 o[et] = __builtin_amdgcn_mfma_f32_16x16x32_bf16(vf, pf.v, o[et], 0, 0, 0); } }
;         const float inv = __builtin_amdgcn_rcpf(den);
;         bf16_t* op = qkv + qtok * QKVC + hh * 64 + 4 * g4;
; #pragma unroll
;         for (int et = 0; et < 4; ++et) { u32x2 wv; wv.x = cvt_pk_bf16(o[et][0] * inv, o[et][1] * inv); wv.y = cvt_pk_bf16(o[et][2] * inv, o[et][3] * inv); *(u32x2*)(op + et * 16) = wv; }
;         if (g4 == 0) lse[qtok * 24 + hh] = mx * 0.6931471805599453f + logf(den);
	v_mfma_f32_16x16x32_bf16 v[70:73], v[80:83], v[66:69], v[72:75]
	v_exp_f32_e32 v80, v55
	s_waitcnt lgkmcnt(4)
	v_mfma_f32_16x16x32_bf16 v[74:77], v[84:87], v[66:69], v[76:79]
	s_nop 2
	v_exp_f32_e32 v78, v54
	v_sub_f32_e32 v54, v56, v50
	v_exp_f32_e32 v86, v54
	s_waitcnt lgkmcnt(1)
	v_mfma_f32_16x16x32_bf16 v[54:57], v[114:117], v[66:69], v[58:61]
	s_nop 2
	v_add_f32_e32 v58, v80, v139
	v_add_f32_e32 v58, v78, v58
	v_add_f32_e32 v87, v86, v58
	s_waitcnt lgkmcnt(0)
	v_mfma_f32_16x16x32_bf16 v[58:61], v[118:121], v[66:69], v[62:65]
	ds_read_b64_tr_b16 v[66:67], v111 offset:52992
	ds_read_b64_tr_b16 v[68:69], v111 offset:55296
	s_nop 0
	v_cvt_pk_bf16_f32 v62, v134, v135
	v_cvt_pk_bf16_f32 v63, v136, v113
	v_cvt_pk_bf16_f32 v64, v137, v138
	v_cvt_pk_bf16_f32 v65, v80, v78
	ds_read_b64_tr_b16 v[80:81], v111 offset:55328
	ds_read_b64_tr_b16 v[78:79], v111 offset:53024
	ds_read_b64_tr_b16 v[82:83], v111 offset:53056
	ds_read_b64_tr_b16 v[114:115], v111 offset:53088
	ds_read_b64_tr_b16 v[84:85], v111 offset:55360
	ds_read_b64_tr_b16 v[116:117], v111 offset:55392
	v_exp_f32_e32 v113, v52
	v_sub_f32_e32 v52, v53, v50
	s_waitcnt lgkmcnt(6)
	v_mfma_f32_16x16x32_bf16 v[66:69], v[66:69], v[62:65], v[70:73]
	s_waitcnt lgkmcnt(4)
	v_mfma_f32_16x16x32_bf16 v[70:73], v[78:81], v[62:65], v[74:77]
	s_nop 2
	v_exp_f32_e32 v74, v52
	s_waitcnt lgkmcnt(1)
	v_mfma_f32_16x16x32_bf16 v[52:55], v[82:85], v[62:65], v[54:57]
	s_nop 2
	v_add_f32_e32 v56, v113, v87
	v_add_f32_e32 v56, v74, v56
	v_add_f32_e32 v87, v49, v56
	s_waitcnt lgkmcnt(0)
	v_mfma_f32_16x16x32_bf16 v[56:59], v[114:117], v[62:65], v[58:61]
	v_mov_b32_e32 v62, v185
	v_mov_b32_e32 v63, v185
	s_nop 0
	v_cvt_pk_bf16_f32 v61, v74, v49
	ds_read_b64_tr_b16 v[74:75], v111 offset:57600
	ds_read_b64_tr_b16 v[76:77], v111 offset:59904
	ds_bpermute_b32 v49, v48, v87
	v_cvt_pk_bf16_f32 v60, v86, v113
	ds_read_b64_tr_b16 v[80:81], v111 offset:59936
	ds_read_b64_tr_b16 v[78:79], v111 offset:57632
	ds_read_b64_tr_b16 v[82:83], v111 offset:57664
	ds_read_b64_tr_b16 v[114:115], v111 offset:57696
	ds_read_b64_tr_b16 v[84:85], v111 offset:59968
	ds_read_b64_tr_b16 v[116:117], v111 offset:60000
	s_waitcnt lgkmcnt(7)
	v_mfma_f32_16x16x32_bf16 v[64:67], v[74:77], v[60:63], v[66:69]
	v_lshl_or_b32 v48, v101, 6, v106
	v_mov_b32_e32 v101, v185
	s_waitcnt lgkmcnt(4)
	v_mfma_f32_16x16x32_bf16 v[68:71], v[78:81], v[60:63], v[70:73]
	s_nop 2
	v_add_f32_e32 v72, v87, v49
	ds_bpermute_b32 v51, v51, v72
	v_ashrrev_i32_e32 v49, 31, v48
	v_lshlrev_b64 v[48:49], s24, v[48:49]
	s_waitcnt lgkmcnt(2)
	v_mfma_f32_16x16x32_bf16 v[52:55], v[82:85], v[60:63], v[52:55]
	v_lshl_add_u64 v[48:49], s[34:35], 0, v[48:49]
	s_waitcnt lgkmcnt(0)
	v_add_f32_e32 v51, v72, v51
	v_mfma_f32_16x16x32_bf16 v[56:59], v[114:117], v[60:63], v[56:59]
	v_mov_b64_e32 v[62:63], s[6:7]
	v_mad_u64_u32 v[62:63], s[34:35], v48, s93, v[62:63]
	v_rcp_f32_e32 v60, v51
	v_mov_b32_e32 v72, v63
	v_mad_u64_u32 v[72:73], s[34:35], v49, s93, v[72:73]
	s_lshl_b32 s34, s52, 6
	v_mov_b32_e32 v63, v72
	s_ashr_i32 s35, s34, 31
	v_lshl_add_u64 v[62:63], s[34:35], 1, v[62:63]
	v_pk_mul_f32 v[64:65], v[60:61], v[64:65] op_sel_hi:[0,1]
	v_pk_mul_f32 v[66:67], v[60:61], v[66:67] op_sel_hi:[0,1]
	v_pk_mul_f32 v[52:53], v[60:61], v[52:53] op_sel_hi:[0,1]
	v_pk_mul_f32 v[54:55], v[60:61], v[54:55] op_sel_hi:[0,1]
	v_lshl_add_u64 v[62:63], v[62:63], 0, v[100:101]
	v_cvt_pk_bf16_f32 v64, v64, v65
	v_cvt_pk_bf16_f32 v65, v66, v67
	v_cvt_pk_bf16_f32 v52, v52, v53
	v_cvt_pk_bf16_f32 v53, v54, v55
	global_store_dwordx2 v[62:63], v[64:65], off
	v_pk_mul_f32 v[64:65], v[60:61], v[68:69] op_sel_hi:[0,1]
	v_pk_mul_f32 v[66:67], v[60:61], v[70:71] op_sel_hi:[0,1]
	global_store_dwordx2 v[62:63], v[52:53], off offset:64
	v_pk_mul_f32 v[52:53], v[60:61], v[56:57] op_sel_hi:[0,1]
	v_pk_mul_f32 v[54:55], v[60:61], v[58:59] op_sel_hi:[0,1]
	v_cvt_pk_bf16_f32 v64, v64, v65
	v_cvt_pk_bf16_f32 v65, v66, v67
	v_cvt_pk_bf16_f32 v52, v52, v53
	v_cvt_pk_bf16_f32 v53, v54, v55
	global_store_dwordx2 v[62:63], v[64:65], off offset:32
	global_store_dwordx2 v[62:63], v[52:53], off offset:96
	s_and_saveexec_b64 s[58:59], s[10:11]
	s_cbranch_execz .LBB0_49
	s_mov_b32 s24, 0x800000
	v_cmp_gt_f32_e32 vcc, s24, v51
	s_mov_b32 s24, 0x3f317217
	s_ashr_i32 s53, s52, 31
	v_cndmask_b32_e64 v52, 0, 32, vcc
	v_ldexp_f32 v51, v51, v52
	v_log_f32_e32 v51, v51
	v_cndmask_b32_e32 v52, 0, v140, vcc
	v_mul_f32_e32 v53, 0x3f317217, v51
	v_fma_f32 v53, v51, s24, -v53
	v_fmac_f32_e32 v53, 0x3377d1cf, v51
	v_fmac_f32_e32 v53, 0x3f317217, v51
	v_cmp_lt_f32_e64 vcc, |v51|, s70
	s_nop 1
	v_cndmask_b32_e32 v51, v51, v53, vcc
	v_sub_f32_e32 v52, v51, v52
	v_fmac_f32_e32 v52, 0x3f317218, v50
	v_mov_b64_e32 v[50:51], s[0:1]
	v_mad_u64_u32 v[50:51], s[34:35], v48, s92, v[50:51]
	v_mov_b32_e32 v48, v51
	v_mad_u64_u32 v[48:49], s[34:35], v49, s92, v[48:49]
	v_mov_b32_e32 v51, v48
	v_lshl_add_u64 v[48:49], s[52:53], 2, v[50:51]
	global_store_dword v[48:49], v52, off
	s_branch .LBB0_49

; __device__ void filter_phase(unsigned char* smem, const Params& p, int l) {
;     ...
;             float accv[16];
; #pragma unroll
;             for (int i = 0; i < 16; ++i) accv[i] = 0.f;
; #pragma unroll 2
;             for (int k = 0; k < 64; ++k) { const float wv = wout[(size_t)k * 2048 + cb * 512 + c];
; #pragma unroll
;                 for (int i = 0; i < 16; ++i) accv[i] += h3[(half * 16 + i) * 64 + k] * wv; }
.LBB0_281:
	s_lshl_b32 s13, s22, 12
	s_xor_b64 s[18:19], s[20:21], -1
	s_add_i32 s13, s13, 0
	s_mov_b32 s20, 0
	v_mov_b64_e32 v[18:19], v[6:7]
	s_mov_b32 s100, 0x2000
	s_mov_b32 s101, 0
	s_mov_b32 s29, 0
	s_mov_b32 s28, 0x4000
	s_mov_b32 s99, 3
	v_lshl_add_u64 v[74:75], v[18:19], 0, s[100:101]
	global_load_dword v66, v[18:19], off
	global_load_dword v67, v[74:75], off
	v_lshl_add_u64 v[18:19], v[18:19], 0, s[28:29]
	v_lshl_add_u64 v[74:75], v[18:19], 0, s[100:101]
	global_load_dword v68, v[18:19], off
	global_load_dword v69, v[74:75], off
	v_lshl_add_u64 v[18:19], v[18:19], 0, s[28:29]
	v_lshl_add_u64 v[74:75], v[18:19], 0, s[100:101]
	global_load_dword v70, v[18:19], off
	global_load_dword v71, v[74:75], off
	v_lshl_add_u64 v[18:19], v[18:19], 0, s[28:29]
	v_mov_b32_e32 v78, 0
	v_mov_b32_e32 v79, 0
	v_mov_b32_e32 v80, 0
	v_mov_b32_e32 v81, 0
	v_mov_b32_e32 v82, 0
	v_mov_b32_e32 v83, 0
	v_mov_b32_e32 v84, 0
	v_mov_b32_e32 v85, 0
	v_mov_b32_e32 v86, 0
	v_mov_b32_e32 v87, 0
	v_mov_b32_e32 v88, 0
	v_mov_b32_e32 v89, 0
	v_mov_b32_e32 v90, 0
	v_mov_b32_e32 v91, 0
	v_mov_b32_e32 v92, 0
	v_mov_b32_e32 v93, 0
	v_mov_b32_e32 v94, 0
	v_mov_b32_e32 v95, 0
	v_mov_b32_e32 v96, 0
	v_mov_b32_e32 v97, 0
	v_mov_b32_e32 v98, 0
	v_mov_b32_e32 v99, 0
	v_mov_b32_e32 v100, 0
	v_mov_b32_e32 v101, 0
	v_mov_b32_e32 v102, 0
	v_mov_b32_e32 v103, 0
	v_mov_b32_e32 v104, 0
	v_mov_b32_e32 v105, 0
	v_mov_b32_e32 v106, 0
	v_mov_b32_e32 v107, 0
	v_mov_b32_e32 v108, 0
	v_mov_b32_e32 v109, 0
.Lfp_loop:
	s_add_i32 s21, s13, s20
	v_mov_b32_e32 v33, s21
	v_add_u32_e32 v76, 0x800, v33
	v_lshl_add_u64 v[74:75], v[18:19], 0, s[100:101]
	global_load_dword v72, v[18:19], off
	global_load_dword v73, v[74:75], off
	s_cmp_lt_u32 s99, 31
	s_cselect_b32 s28, 0x4000, 0
	s_add_i32 s99, s99, 1
	v_lshl_add_u64 v[18:19], v[18:19], 0, s[28:29]
	ds_read2_b64 v[34:37], v33 offset0:0 offset1:32
	ds_read2_b64 v[38:41], v33 offset0:64 offset1:96
	ds_read2_b64 v[42:45], v33 offset0:128 offset1:160
	ds_read2_b64 v[46:49], v33 offset0:192 offset1:224
	ds_read2_b64 v[50:53], v76 offset0:0 offset1:32
	ds_read2_b64 v[54:57], v76 offset0:64 offset1:96
	ds_read2_b64 v[58:61], v76 offset0:128 offset1:160
	ds_read2_b64 v[62:65], v76 offset0:192 offset1:224
	s_waitcnt vmcnt(6)
	s_waitcnt lgkmcnt(7)
	v_pk_fma_f32 v[78:79], v[66:67], v[34:35], v[78:79]
	v_pk_fma_f32 v[80:81], v[66:67], v[36:37], v[80:81]
	s_waitcnt lgkmcnt(6)
	v_pk_fma_f32 v[82:83], v[66:67], v[38:39], v[82:83]
	v_pk_fma_f32 v[84:85], v[66:67], v[40:41], v[84:85]
	s_waitcnt lgkmcnt(5)
	v_pk_fma_f32 v[86:87], v[66:67], v[42:43], v[86:87]
	v_pk_fma_f32 v[88:89], v[66:67], v[44:45], v[88:89]
	s_waitcnt lgkmcnt(4)
	v_pk_fma_f32 v[90:91], v[66:67], v[46:47], v[90:91]
	v_pk_fma_f32 v[92:93], v[66:67], v[48:49], v[92:93]
	s_waitcnt lgkmcnt(3)
	v_pk_fma_f32 v[94:95], v[66:67], v[50:51], v[94:95]
	v_pk_fma_f32 v[96:97], v[66:67], v[52:53], v[96:97]
	s_waitcnt lgkmcnt(2)
	v_pk_fma_f32 v[98:99], v[66:67], v[54:55], v[98:99]
	v_pk_fma_f32 v[100:101], v[66:67], v[56:57], v[100:101]
	s_waitcnt lgkmcnt(1)
	v_pk_fma_f32 v[102:103], v[66:67], v[58:59], v[102:103]
	v_pk_fma_f32 v[104:105], v[66:67], v[60:61], v[104:105]
	s_waitcnt lgkmcnt(0)
	v_pk_fma_f32 v[106:107], v[66:67], v[62:63], v[106:107]
	v_pk_fma_f32 v[108:109], v[66:67], v[64:65], v[108:109]
	v_lshl_add_u64 v[74:75], v[18:19], 0, s[100:101]
	global_load_dword v66, v[18:19], off
	global_load_dword v67, v[74:75], off
	s_cmp_lt_u32 s99, 31
	s_cselect_b32 s28, 0x4000, 0
	s_add_i32 s99, s99, 1
	v_lshl_add_u64 v[18:19], v[18:19], 0, s[28:29]
	ds_read2_b64 v[34:37], v33 offset0:1 offset1:33
	ds_read2_b64 v[38:41], v33 offset0:65 offset1:97
	ds_read2_b64 v[42:45], v33 offset0:129 offset1:161
	ds_read2_b64 v[46:49], v33 offset0:193 offset1:225
	ds_read2_b64 v[50:53], v76 offset0:1 offset1:33
	ds_read2_b64 v[54:57], v76 offset0:65 offset1:97
	ds_read2_b64 v[58:61], v76 offset0:129 offset1:161
	ds_read2_b64 v[62:65], v76 offset0:193 offset1:225
	s_waitcnt vmcnt(6)
	s_waitcnt lgkmcnt(7)
	v_pk_fma_f32 v[78:79], v[68:69], v[34:35], v[78:79]
	v_pk_fma_f32 v[80:81], v[68:69], v[36:37], v[80:81]
	s_waitcnt lgkmcnt(6)
	v_pk_fma_f32 v[82:83], v[68:69], v[38:39], v[82:83]
	v_pk_fma_f32 v[84:85], v[68:69], v[40:41], v[84:85]
	s_waitcnt lgkmcnt(5)
	v_pk_fma_f32 v[86:87], v[68:69], v[42:43], v[86:87]
	v_pk_fma_f32 v[88:89], v[68:69], v[44:45], v[88:89]
	s_waitcnt lgkmcnt(4)
	v_pk_fma_f32 v[90:91], v[68:69], v[46:47], v[90:91]
	v_pk_fma_f32 v[92:93], v[68:69], v[48:49], v[92:93]
	s_waitcnt lgkmcnt(3)
	v_pk_fma_f32 v[94:95], v[68:69], v[50:51], v[94:95]
	v_pk_fma_f32 v[96:97], v[68:69], v[52:53], v[96:97]
	s_waitcnt lgkmcnt(2)
	v_pk_fma_f32 v[98:99], v[68:69], v[54:55], v[98:99]
	v_pk_fma_f32 v[100:101], v[68:69], v[56:57], v[100:101]
	s_waitcnt lgkmcnt(1)
	v_pk_fma_f32 v[102:103], v[68:69], v[58:59], v[102:103]
	v_pk_fma_f32 v[104:105], v[68:69], v[60:61], v[104:105]
	s_waitcnt lgkmcnt(0)
	v_pk_fma_f32 v[106:107], v[68:69], v[62:63], v[106:107]
	v_pk_fma_f32 v[108:109], v[68:69], v[64:65], v[108:109]
	v_lshl_add_u64 v[74:75], v[18:19], 0, s[100:101]
	global_load_dword v68, v[18:19], off
	global_load_dword v69, v[74:75], off
	s_cmp_lt_u32 s99, 31
	s_cselect_b32 s28, 0x4000, 0
	s_add_i32 s99, s99, 1
	v_lshl_add_u64 v[18:19], v[18:19], 0, s[28:29]
	ds_read2_b64 v[34:37], v33 offset0:2 offset1:34
	ds_read2_b64 v[38:41], v33 offset0:66 offset1:98
	ds_read2_b64 v[42:45], v33 offset0:130 offset1:162
	ds_read2_b64 v[46:49], v33 offset0:194 offset1:226
	ds_read2_b64 v[50:53], v76 offset0:2 offset1:34
	ds_read2_b64 v[54:57], v76 offset0:66 offset1:98
	ds_read2_b64 v[58:61], v76 offset0:130 offset1:162
	ds_read2_b64 v[62:65], v76 offset0:194 offset1:226
	s_waitcnt vmcnt(6)
; __device__ void filter_phase(unsigned char* smem, const Params& p, int l) {
;     ...
;             for (int k = 0; k < 64; ++k) { const float wv = wout[(size_t)k * 2048 + cb * 512 + c];
; #pragma unroll
;                 for (int i = 0; i < 16; ++i) accv[i] += h3[(half * 16 + i) * 64 + k] * wv; }
; #pragma unroll
;             for (int i = 0; i < 16; ++i) { const int pos = pb * 32 + half * 16 + i; const float t = (float)pos / 2047.0f; const float val = accv[i] * (expf(-t * delta) + 0.05f);
	s_waitcnt lgkmcnt(7)
	v_pk_fma_f32 v[78:79], v[70:71], v[34:35], v[78:79]
	v_pk_fma_f32 v[80:81], v[70:71], v[36:37], v[80:81]
	s_waitcnt lgkmcnt(6)
	v_pk_fma_f32 v[82:83], v[70:71], v[38:39], v[82:83]
	v_pk_fma_f32 v[84:85], v[70:71], v[40:41], v[84:85]
	s_waitcnt lgkmcnt(5)
	v_pk_fma_f32 v[86:87], v[70:71], v[42:43], v[86:87]
	v_pk_fma_f32 v[88:89], v[70:71], v[44:45], v[88:89]
	s_waitcnt lgkmcnt(4)
	v_pk_fma_f32 v[90:91], v[70:71], v[46:47], v[90:91]
	v_pk_fma_f32 v[92:93], v[70:71], v[48:49], v[92:93]
	s_waitcnt lgkmcnt(3)
	v_pk_fma_f32 v[94:95], v[70:71], v[50:51], v[94:95]
	v_pk_fma_f32 v[96:97], v[70:71], v[52:53], v[96:97]
	s_waitcnt lgkmcnt(2)
	v_pk_fma_f32 v[98:99], v[70:71], v[54:55], v[98:99]
	v_pk_fma_f32 v[100:101], v[70:71], v[56:57], v[100:101]
	s_waitcnt lgkmcnt(1)
	v_pk_fma_f32 v[102:103], v[70:71], v[58:59], v[102:103]
	v_pk_fma_f32 v[104:105], v[70:71], v[60:61], v[104:105]
	s_waitcnt lgkmcnt(0)
	v_pk_fma_f32 v[106:107], v[70:71], v[62:63], v[106:107]
	v_pk_fma_f32 v[108:109], v[70:71], v[64:65], v[108:109]
	v_lshl_add_u64 v[74:75], v[18:19], 0, s[100:101]
	global_load_dword v70, v[18:19], off
	global_load_dword v71, v[74:75], off
	s_cmp_lt_u32 s99, 31
	s_cselect_b32 s28, 0x4000, 0
	s_add_i32 s99, s99, 1
	v_lshl_add_u64 v[18:19], v[18:19], 0, s[28:29]
	ds_read2_b64 v[34:37], v33 offset0:3 offset1:35
	ds_read2_b64 v[38:41], v33 offset0:67 offset1:99
	ds_read2_b64 v[42:45], v33 offset0:131 offset1:163
	ds_read2_b64 v[46:49], v33 offset0:195 offset1:227
	ds_read2_b64 v[50:53], v76 offset0:3 offset1:35
	ds_read2_b64 v[54:57], v76 offset0:67 offset1:99
	ds_read2_b64 v[58:61], v76 offset0:131 offset1:163
	ds_read2_b64 v[62:65], v76 offset0:195 offset1:227
	s_waitcnt vmcnt(6)
	s_waitcnt lgkmcnt(7)
	v_pk_fma_f32 v[78:79], v[72:73], v[34:35], v[78:79]
	v_pk_fma_f32 v[80:81], v[72:73], v[36:37], v[80:81]
	s_waitcnt lgkmcnt(6)
	v_pk_fma_f32 v[82:83], v[72:73], v[38:39], v[82:83]
	v_pk_fma_f32 v[84:85], v[72:73], v[40:41], v[84:85]
	s_waitcnt lgkmcnt(5)
	v_pk_fma_f32 v[86:87], v[72:73], v[42:43], v[86:87]
	v_pk_fma_f32 v[88:89], v[72:73], v[44:45], v[88:89]
	s_waitcnt lgkmcnt(4)
	v_pk_fma_f32 v[90:91], v[72:73], v[46:47], v[90:91]
	v_pk_fma_f32 v[92:93], v[72:73], v[48:49], v[92:93]
	s_waitcnt lgkmcnt(3)
	v_pk_fma_f32 v[94:95], v[72:73], v[50:51], v[94:95]
	v_pk_fma_f32 v[96:97], v[72:73], v[52:53], v[96:97]
	s_waitcnt lgkmcnt(2)
	v_pk_fma_f32 v[98:99], v[72:73], v[54:55], v[98:99]
	v_pk_fma_f32 v[100:101], v[72:73], v[56:57], v[100:101]
	s_waitcnt lgkmcnt(1)
	v_pk_fma_f32 v[102:103], v[72:73], v[58:59], v[102:103]
	v_pk_fma_f32 v[104:105], v[72:73], v[60:61], v[104:105]
	s_waitcnt lgkmcnt(0)
	v_pk_fma_f32 v[106:107], v[72:73], v[62:63], v[106:107]
	v_pk_fma_f32 v[108:109], v[72:73], v[64:65], v[108:109]
	s_add_i32 s20, s20, 32
	s_cmpk_eq_i32 s20, 0x100
	s_cbranch_scc0 .Lfp_loop
	s_waitcnt vmcnt(0)
	v_add_f32_e32 v26, v78, v79
	v_add_f32_e32 v27, v80, v81
	v_add_f32_e32 v24, v82, v83
	v_add_f32_e32 v25, v84, v85
	v_add_f32_e32 v22, v86, v87
	v_add_f32_e32 v23, v88, v89
	v_add_f32_e32 v20, v90, v91
	v_add_f32_e32 v21, v92, v93
	v_add_f32_e32 v16, v94, v95
	v_add_f32_e32 v17, v96, v97
	v_add_f32_e32 v14, v98, v99
	v_add_f32_e32 v15, v100, v101
	v_add_f32_e32 v12, v102, v103
	v_add_f32_e32 v13, v104, v105
	v_add_f32_e32 v10, v106, v107
	v_add_f32_e32 v11, v108, v109
	s_mov_b64 s[28:29], 0x4000
	s_lshl_b32 s24, s22, 4
	s_or_b32 s13, s24, s12
	v_cvt_f32_i32_e32 v18, s13
	s_cmp_eq_u32 s13, 0
	v_div_scale_f32 v19, s[20:21], s95, s95, v18
	v_rcp_f32_e32 v33, v19
	v_div_scale_f32 v34, vcc, v18, s95, v18
	s_cselect_b64 s[20:21], -1, 0
	v_fma_f32 v35, -v19, v33, 1.0
	v_fmac_f32_e32 v33, v35, v33
	v_mul_f32_e32 v35, v34, v33
	v_fma_f32 v36, -v19, v35, v34
	v_fmac_f32_e32 v35, v36, v33
	v_fma_f32 v19, -v19, v35, v34
	v_div_fmas_f32 v19, v19, v33, v35
	v_div_fixup_f32 v18, v19, s95, v18
	v_mul_f32_e64 v18, |v29|, v18
	v_mul_f32_e32 v19, 0x3fb8aa3b, v18
	v_fma_f32 v33, v18, s71, -v19
	v_rndne_f32_e32 v34, v19
	v_fmac_f32_e32 v33, 0x32a5705f, v18
	v_sub_f32_e32 v19, v19, v34
	s_or_b32 s22, s13, 1
	v_add_f32_e32 v19, v19, v33
	v_cvt_f32_i32_e32 v33, s22
	v_exp_f32_e32 v19, v19
	v_cvt_i32_f32_e32 v34, v34
	v_cmp_ngt_f32_e32 vcc, s96, v18
	v_div_scale_f32 v35, s[22:23], s95, s95, v33
	v_rcp_f32_e32 v36, v35
	v_ldexp_f32 v19, v19, v34
	v_cndmask_b32_e32 v19, 0, v19, vcc
	s_or_b32 s23, s13, 2
	v_fma_f32 v34, -v35, v36, 1.0
	v_fmac_f32_e32 v36, v34, v36
	v_div_scale_f32 v34, vcc, v33, s95, v33
	v_mul_f32_e32 v37, v34, v36
	v_fma_f32 v38, -v35, v37, v34
	v_fmac_f32_e32 v37, v38, v36
	v_fma_f32 v34, -v35, v37, v34
	v_div_fmas_f32 v34, v34, v36, v37
	v_div_fixup_f32 v33, v34, s95, v33
	v_mul_f32_e64 v33, |v29|, v33
	v_mul_f32_e32 v34, 0x3fb8aa3b, v33
	v_fma_f32 v35, v33, s71, -v34
	v_rndne_f32_e32 v36, v34
	v_fmac_f32_e32 v35, 0x32a5705f, v33
	v_sub_f32_e32 v34, v34, v36
	v_add_f32_e32 v34, v34, v35
	v_exp_f32_e32 v35, v34
	v_cvt_i32_f32_e32 v36, v36
	v_cmp_nlt_f32_e32 vcc, s97, v18
	s_mov_b32 s22, 1
	v_ldexp_f32 v35, v35, v36
	v_cvt_f32_i32_e32 v36, s23
	v_cndmask_b32_e32 v34, v242, v19, vcc
	v_cmp_ngt_f32_e32 vcc, s96, v33
	s_or_b32 s23, s13, 3
	v_lshl_add_u64 v[18:19], s[24:25], 2, v[8:9]
	v_cndmask_b32_e32 v35, 0, v35, vcc
	v_cmp_nlt_f32_e32 vcc, s97, v33
	v_div_scale_f32 v33, s[28:29], s95, s95, v36
	v_rcp_f32_e32 v37, v33
	v_cndmask_b32_e32 v35, v242, v35, vcc
	v_pk_add_f32 v[34:35], v[34:35], s[26:27] op_sel_hi:[1,0]
	s_nop 0
	v_pk_mul_f32 v[34:35], v[34:35], v[26:27]
	v_fma_f32 v27, -v33, v37, 1.0
	v_fmac_f32_e32 v37, v27, v37
	v_div_scale_f32 v27, vcc, v36, s95, v36
	v_mul_f32_e32 v38, v27, v37
	v_fma_f32 v39, -v33, v38, v27
	v_fmac_f32_e32 v38, v39, v37
; __device__ void filter_phase(unsigned char* smem, const Params& p, int l) {
;     ...
;             for (int i = 0; i < 16; ++i) { const int pos = pb * 32 + half * 16 + i; const float t = (float)pos / 2047.0f; const float val = accv[i] * (expf(-t * delta) + 0.05f);
;                 dst[half * 16 + i] = val; if (!(dir == 1 && pos == 0)) asum += fabsf(val); }
	v_fma_f32 v27, -v33, v38, v27
	v_div_fmas_f32 v27, v27, v37, v38
	v_div_fixup_f32 v27, v27, s95, v36
	v_mul_f32_e64 v27, |v29|, v27
	v_mul_f32_e32 v33, 0x3fb8aa3b, v27
	v_fma_f32 v36, v27, s71, -v33
	v_rndne_f32_e32 v37, v33
	v_fmac_f32_e32 v36, 0x32a5705f, v27
	v_sub_f32_e32 v33, v33, v37
	v_add_f32_e32 v33, v33, v36
	v_cvt_f32_i32_e32 v36, s23
	v_exp_f32_e32 v33, v33
	v_cvt_i32_f32_e32 v37, v37
	v_add_f32_e64 v26, v32, |v34|
	v_div_scale_f32 v38, s[28:29], s95, s95, v36
	v_rcp_f32_e32 v39, v38
	s_and_b64 vcc, s[16:17], s[20:21]
	v_cndmask_b32_e32 v26, v26, v32, vcc
	v_add_f32_e64 v32, |v35|, v26
	v_ldexp_f32 v26, v33, v37
	v_fma_f32 v33, -v38, v39, 1.0
	v_fmac_f32_e32 v39, v33, v39
	v_div_scale_f32 v33, vcc, v36, s95, v36
	v_mul_f32_e32 v37, v33, v39
	v_fma_f32 v40, -v38, v37, v33
	v_fmac_f32_e32 v37, v40, v39
	v_fma_f32 v33, -v38, v37, v33
	v_div_fmas_f32 v33, v33, v39, v37
	v_div_fixup_f32 v33, v33, s95, v36
	v_mul_f32_e64 v33, |v29|, v33
	v_mul_f32_e32 v36, 0x3fb8aa3b, v33
	v_fma_f32 v37, v33, s71, -v36
	v_rndne_f32_e32 v38, v36
	v_fmac_f32_e32 v37, 0x32a5705f, v33
	v_sub_f32_e32 v36, v36, v38
	v_add_f32_e32 v36, v36, v37
	v_exp_f32_e32 v36, v36
	v_cvt_i32_f32_e32 v37, v38
	s_or_b32 s20, s13, 4
	v_cvt_f32_i32_e32 v38, s20
	v_cmp_ngt_f32_e32 vcc, s96, v27
	s_nop 1
	v_cndmask_b32_e32 v26, 0, v26, vcc
	v_cmp_nlt_f32_e32 vcc, s97, v27
	v_ldexp_f32 v27, v36, v37
	s_nop 0
	v_cndmask_b32_e32 v26, v242, v26, vcc
	v_cmp_ngt_f32_e32 vcc, s96, v33
	s_nop 1
	v_cndmask_b32_e32 v27, 0, v27, vcc
	v_cmp_nlt_f32_e32 vcc, s97, v33
	v_div_scale_f32 v33, s[20:21], s95, s95, v38
	v_rcp_f32_e32 v39, v33
	v_cndmask_b32_e32 v27, v242, v27, vcc
	v_pk_add_f32 v[26:27], v[26:27], s[26:27] op_sel_hi:[1,0]
	s_or_b32 s20, s13, 5
	v_pk_mul_f32 v[36:37], v[26:27], v[24:25]
	v_fma_f32 v25, -v33, v39, 1.0
	v_fmac_f32_e32 v39, v25, v39
	v_div_scale_f32 v25, vcc, v38, s95, v38
	v_mul_f32_e32 v26, v25, v39
	v_fma_f32 v27, -v33, v26, v25
	v_fmac_f32_e32 v26, v27, v39
	v_fma_f32 v25, -v33, v26, v25
	v_div_fmas_f32 v25, v25, v39, v26
	v_div_fixup_f32 v25, v25, s95, v38
	v_mul_f32_e64 v25, |v29|, v25
	v_mul_f32_e32 v26, 0x3fb8aa3b, v25
	v_add_f32_e64 v24, |v36|, v32
	v_fma_f32 v27, v25, s71, -v26
	v_rndne_f32_e32 v32, v26
	v_fmac_f32_e32 v27, 0x32a5705f, v25
	v_sub_f32_e32 v26, v26, v32
	v_add_f32_e32 v26, v26, v27
	v_cvt_f32_i32_e32 v27, s20
	v_exp_f32_e32 v26, v26
	v_cvt_i32_f32_e32 v32, v32
	global_store_dwordx4 v[18:19], v[34:37], off
	v_div_scale_f32 v33, s[20:21], s95, s95, v27
	v_rcp_f32_e32 v38, v33
	v_add_f32_e64 v34, |v37|, v24
	v_ldexp_f32 v24, v26, v32
	s_or_b32 s20, s13, 6
	v_fma_f32 v26, -v33, v38, 1.0
	v_fmac_f32_e32 v38, v26, v38
	v_div_scale_f32 v26, vcc, v27, s95, v27
	v_mul_f32_e32 v32, v26, v38
	v_fma_f32 v35, -v33, v32, v26
	v_fmac_f32_e32 v32, v35, v38
	v_fma_f32 v26, -v33, v32, v26
	v_div_fmas_f32 v26, v26, v38, v32
	v_div_fixup_f32 v26, v26, s95, v27
	v_mul_f32_e64 v26, |v29|, v26
	v_mul_f32_e32 v27, 0x3fb8aa3b, v26
	v_fma_f32 v32, v26, s71, -v27
	v_rndne_f32_e32 v33, v27
	v_fmac_f32_e32 v32, 0x32a5705f, v26
	v_sub_f32_e32 v27, v27, v33
	v_add_f32_e32 v27, v27, v32
	v_exp_f32_e32 v27, v27
	v_cvt_i32_f32_e32 v32, v33
	v_cmp_ngt_f32_e32 vcc, s96, v25
	s_nop 1
	v_cndmask_b32_e32 v24, 0, v24, vcc
	v_cmp_nlt_f32_e32 vcc, s97, v25
	v_ldexp_f32 v25, v27, v32
	v_cvt_f32_i32_e32 v27, s20
	v_cndmask_b32_e32 v24, v242, v24, vcc
	v_cmp_ngt_f32_e32 vcc, s96, v26
	v_div_scale_f32 v32, s[20:21], s95, s95, v27
	v_rcp_f32_e32 v33, v32
	v_cndmask_b32_e32 v25, 0, v25, vcc
	v_cmp_nlt_f32_e32 vcc, s97, v26
	s_or_b32 s20, s13, 7
	s_nop 0
	v_cndmask_b32_e32 v25, v242, v25, vcc
	v_pk_add_f32 v[24:25], v[24:25], s[26:27] op_sel_hi:[1,0]
	s_nop 0
	v_pk_mul_f32 v[22:23], v[24:25], v[22:23]
	v_fma_f32 v24, -v32, v33, 1.0
	v_fmac_f32_e32 v33, v24, v33
	v_div_scale_f32 v24, vcc, v27, s95, v27
	v_mul_f32_e32 v25, v24, v33
	v_fma_f32 v26, -v32, v25, v24
	v_fmac_f32_e32 v25, v26, v33
	v_fma_f32 v24, -v32, v25, v24
	v_div_fmas_f32 v24, v24, v33, v25
	v_div_fixup_f32 v24, v24, s95, v27
	v_mul_f32_e64 v24, |v29|, v24
	v_mul_f32_e32 v25, 0x3fb8aa3b, v24
	v_fma_f32 v26, v24, s71, -v25
	v_rndne_f32_e32 v27, v25
	v_fmac_f32_e32 v26, 0x32a5705f, v24
	v_sub_f32_e32 v25, v25, v27
	v_add_f32_e32 v25, v25, v26
	v_cvt_f32_i32_e32 v26, s20
	v_exp_f32_e32 v25, v25
	v_cvt_i32_f32_e32 v27, v27
	v_add_f32_e64 v34, |v22|, v34
	v_div_scale_f32 v32, s[20:21], s95, s95, v26
	v_rcp_f32_e32 v33, v32
	v_ldexp_f32 v25, v25, v27
	s_or_b32 s20, s13, 8
	v_add_f32_e64 v34, |v23|, v34
	v_fma_f32 v27, -v32, v33, 1.0
	v_fmac_f32_e32 v33, v27, v33
	v_div_scale_f32 v27, vcc, v26, s95, v26
	v_mul_f32_e32 v35, v27, v33
	v_fma_f32 v36, -v32, v35, v27
	v_fmac_f32_e32 v35, v36, v33
	v_fma_f32 v27, -v32, v35, v27
	v_div_fmas_f32 v27, v27, v33, v35
	v_div_fixup_f32 v26, v27, s95, v26
	v_mul_f32_e64 v26, |v29|, v26
	v_mul_f32_e32 v27, 0x3fb8aa3b, v26
	v_fma_f32 v32, v26, s71, -v27
	v_rndne_f32_e32 v33, v27
	v_fmac_f32_e32 v32, 0x32a5705f, v26
	v_sub_f32_e32 v27, v27, v33
	v_add_f32_e32 v27, v27, v32
	v_exp_f32_e32 v27, v27
	v_cvt_i32_f32_e32 v32, v33
	v_cmp_ngt_f32_e32 vcc, s96, v24
	s_nop 1
	v_cndmask_b32_e32 v25, 0, v25, vcc
	v_cmp_nlt_f32_e32 vcc, s97, v24
	s_nop 1
	v_cndmask_b32_e32 v24, v242, v25, vcc
	v_ldexp_f32 v25, v27, v32
	v_cvt_f32_i32_e32 v27, s20
	v_cmp_ngt_f32_e32 vcc, s96, v26
	s_nop 1
	v_cndmask_b32_e32 v25, 0, v25, vcc
	v_cmp_nlt_f32_e32 vcc, s97, v26
	v_div_scale_f32 v26, s[20:21], s95, s95, v27
	v_rcp_f32_e32 v32, v26
	v_cndmask_b32_e32 v25, v242, v25, vcc
	v_pk_add_f32 v[24:25], v[24:25], s[26:27] op_sel_hi:[1,0]
	s_or_b32 s20, s13, 9
	v_pk_mul_f32 v[24:25], v[24:25], v[20:21]
	v_fma_f32 v21, -v26, v32, 1.0
; __device__ void filter_phase(unsigned char* smem, const Params& p, int l) {
;     ...
;             for (int i = 0; i < 16; ++i) { const int pos = pb * 32 + half * 16 + i; const float t = (float)pos / 2047.0f; const float val = accv[i] * (expf(-t * delta) + 0.05f);
;                 dst[half * 16 + i] = val; if (!(dir == 1 && pos == 0)) asum += fabsf(val); }
	v_fmac_f32_e32 v32, v21, v32
	v_div_scale_f32 v21, vcc, v27, s95, v27
	v_mul_f32_e32 v33, v21, v32
	v_add_f32_e64 v20, |v24|, v34
	v_fma_f32 v34, -v26, v33, v21
	v_fmac_f32_e32 v33, v34, v32
	v_fma_f32 v21, -v26, v33, v21
	v_div_fmas_f32 v21, v21, v32, v33
	v_div_fixup_f32 v21, v21, s95, v27
	v_mul_f32_e64 v21, |v29|, v21
	v_mul_f32_e32 v26, 0x3fb8aa3b, v21
	v_fma_f32 v27, v21, s71, -v26
	v_rndne_f32_e32 v32, v26
	v_fmac_f32_e32 v27, 0x32a5705f, v21
	v_sub_f32_e32 v26, v26, v32
	v_add_f32_e32 v26, v26, v27
	v_cvt_f32_i32_e32 v27, s20
	global_store_dwordx4 v[18:19], v[22:25], off offset:16
	v_exp_f32_e32 v26, v26
	v_cvt_i32_f32_e32 v32, v32
	v_div_scale_f32 v33, s[20:21], s95, s95, v27
	v_rcp_f32_e32 v34, v33
	v_add_f32_e64 v22, |v25|, v20
	v_ldexp_f32 v20, v26, v32
	s_or_b32 s20, s13, 10
	v_fma_f32 v23, -v33, v34, 1.0
	v_fmac_f32_e32 v34, v23, v34
	v_div_scale_f32 v23, vcc, v27, s95, v27
	v_mul_f32_e32 v24, v23, v34
	v_fma_f32 v25, -v33, v24, v23
	v_fmac_f32_e32 v24, v25, v34
	v_fma_f32 v23, -v33, v24, v23
	v_div_fmas_f32 v23, v23, v34, v24
	v_div_fixup_f32 v23, v23, s95, v27
	v_mul_f32_e64 v23, |v29|, v23
	v_mul_f32_e32 v24, 0x3fb8aa3b, v23
	v_fma_f32 v25, v23, s71, -v24
	v_rndne_f32_e32 v26, v24
	v_fmac_f32_e32 v25, 0x32a5705f, v23
	v_sub_f32_e32 v24, v24, v26
	v_add_f32_e32 v24, v24, v25
	v_exp_f32_e32 v24, v24
	v_cvt_i32_f32_e32 v25, v26
	v_cmp_ngt_f32_e32 vcc, s96, v21
	s_nop 1
	v_cndmask_b32_e32 v20, 0, v20, vcc
	v_cmp_nlt_f32_e32 vcc, s97, v21
	v_ldexp_f32 v21, v24, v25
	v_cvt_f32_i32_e32 v24, s20
	v_cndmask_b32_e32 v20, v242, v20, vcc
	v_cmp_ngt_f32_e32 vcc, s96, v23
	v_div_scale_f32 v25, s[20:21], s95, s95, v24
	v_rcp_f32_e32 v26, v25
	v_cndmask_b32_e32 v21, 0, v21, vcc
	v_cmp_nlt_f32_e32 vcc, s97, v23
	s_or_b32 s20, s13, 11
	s_nop 0
	v_cndmask_b32_e32 v21, v242, v21, vcc
	v_pk_add_f32 v[20:21], v[20:21], s[26:27] op_sel_hi:[1,0]
	s_nop 0
	v_pk_mul_f32 v[20:21], v[20:21], v[16:17]
	v_fma_f32 v16, -v25, v26, 1.0
	v_fmac_f32_e32 v26, v16, v26
	v_div_scale_f32 v16, vcc, v24, s95, v24
	v_mul_f32_e32 v17, v16, v26
	v_fma_f32 v23, -v25, v17, v16
	v_fmac_f32_e32 v17, v23, v26
	v_fma_f32 v16, -v25, v17, v16
	v_div_fmas_f32 v16, v16, v26, v17
	v_div_fixup_f32 v16, v16, s95, v24
	v_mul_f32_e64 v16, |v29|, v16
	v_mul_f32_e32 v17, 0x3fb8aa3b, v16
	v_fma_f32 v23, v16, s71, -v17
	v_rndne_f32_e32 v24, v17
	v_fmac_f32_e32 v23, 0x32a5705f, v16
	v_sub_f32_e32 v17, v17, v24
	v_add_f32_e32 v17, v17, v23
	v_cvt_f32_i32_e32 v23, s20
	v_exp_f32_e32 v17, v17
	v_cvt_i32_f32_e32 v24, v24
	v_add_f32_e64 v22, |v20|, v22
	v_div_scale_f32 v25, s[20:21], s95, s95, v23
	v_rcp_f32_e32 v26, v25
	v_add_f32_e64 v27, |v21|, v22
	v_ldexp_f32 v17, v17, v24
	s_or_b32 s20, s13, 12
	v_fma_f32 v22, -v25, v26, 1.0
	v_fmac_f32_e32 v26, v22, v26
	v_div_scale_f32 v22, vcc, v23, s95, v23
	v_mul_f32_e32 v24, v22, v26
	v_fma_f32 v32, -v25, v24, v22
	v_fmac_f32_e32 v24, v32, v26
	v_fma_f32 v22, -v25, v24, v22
	v_div_fmas_f32 v22, v22, v26, v24
	v_div_fixup_f32 v22, v22, s95, v23
	v_mul_f32_e64 v22, |v29|, v22
	v_mul_f32_e32 v23, 0x3fb8aa3b, v22
	v_fma_f32 v24, v22, s71, -v23
	v_rndne_f32_e32 v25, v23
	v_fmac_f32_e32 v24, 0x32a5705f, v22
	v_sub_f32_e32 v23, v23, v25
	v_add_f32_e32 v23, v23, v24
	v_exp_f32_e32 v23, v23
	v_cvt_i32_f32_e32 v24, v25
	v_cmp_ngt_f32_e32 vcc, s96, v16
	s_nop 1
	v_cndmask_b32_e32 v17, 0, v17, vcc
	v_cmp_nlt_f32_e32 vcc, s97, v16
	s_nop 1
	v_cndmask_b32_e32 v16, v242, v17, vcc
	v_ldexp_f32 v17, v23, v24
	v_cvt_f32_i32_e32 v24, s20
	v_cmp_ngt_f32_e32 vcc, s96, v22
	v_div_scale_f32 v25, s[20:21], s95, s95, v24
	v_rcp_f32_e32 v26, v25
	v_cndmask_b32_e32 v17, 0, v17, vcc
	v_cmp_nlt_f32_e32 vcc, s97, v22
	s_or_b32 s20, s13, 13
	s_nop 0
	v_cndmask_b32_e32 v17, v242, v17, vcc
	v_pk_add_f32 v[16:17], v[16:17], s[26:27] op_sel_hi:[1,0]
	s_nop 0
	v_pk_mul_f32 v[22:23], v[16:17], v[14:15]
	v_fma_f32 v15, -v25, v26, 1.0
	v_fmac_f32_e32 v26, v15, v26
	v_div_scale_f32 v15, vcc, v24, s95, v24
	v_mul_f32_e32 v16, v15, v26
	v_fma_f32 v17, -v25, v16, v15
	v_fmac_f32_e32 v16, v17, v26
; __device__ void filter_phase(unsigned char* smem, const Params& p, int l) {
;     ...
;             for (int i = 0; i < 16; ++i) { const int pos = pb * 32 + half * 16 + i; const float t = (float)pos / 2047.0f; const float val = accv[i] * (expf(-t * delta) + 0.05f);
;                 dst[half * 16 + i] = val; if (!(dir == 1 && pos == 0)) asum += fabsf(val); }
;         }
;         norms[16384 + pb * 2048 + cb * 512 + c] = asum;
	v_fma_f32 v15, -v25, v16, v15
	v_div_fmas_f32 v15, v15, v26, v16
	v_div_fixup_f32 v15, v15, s95, v24
	v_mul_f32_e64 v15, |v29|, v15
	v_mul_f32_e32 v16, 0x3fb8aa3b, v15
	v_fma_f32 v17, v15, s71, -v16
	v_rndne_f32_e32 v24, v16
	v_fmac_f32_e32 v17, 0x32a5705f, v15
	v_sub_f32_e32 v16, v16, v24
	v_add_f32_e32 v16, v16, v17
	v_cvt_f32_i32_e32 v17, s20
	v_exp_f32_e32 v16, v16
	v_cvt_i32_f32_e32 v24, v24
	v_add_f32_e64 v14, |v22|, v27
	v_div_scale_f32 v25, s[20:21], s95, s95, v17
	v_rcp_f32_e32 v26, v25
	global_store_dwordx4 v[18:19], v[20:23], off offset:32
	s_or_b32 s20, s13, 14
	s_or_b32 s13, s13, 15
	v_add_f32_e64 v20, |v23|, v14
	v_ldexp_f32 v14, v16, v24
	v_fma_f32 v16, -v25, v26, 1.0
	v_fmac_f32_e32 v26, v16, v26
	v_div_scale_f32 v16, vcc, v17, s95, v17
	v_mul_f32_e32 v21, v16, v26
	v_fma_f32 v22, -v25, v21, v16
	v_fmac_f32_e32 v21, v22, v26
	v_fma_f32 v16, -v25, v21, v16
	v_div_fmas_f32 v16, v16, v26, v21
	v_div_fixup_f32 v16, v16, s95, v17
	v_mul_f32_e64 v16, |v29|, v16
	v_mul_f32_e32 v17, 0x3fb8aa3b, v16
	v_fma_f32 v21, v16, s71, -v17
	v_rndne_f32_e32 v22, v17
	v_fmac_f32_e32 v21, 0x32a5705f, v16
	v_sub_f32_e32 v17, v17, v22
	v_add_f32_e32 v17, v17, v21
	v_exp_f32_e32 v17, v17
	v_cvt_i32_f32_e32 v21, v22
	v_cmp_ngt_f32_e32 vcc, s96, v15
	s_nop 1
	v_cndmask_b32_e32 v14, 0, v14, vcc
	v_cmp_nlt_f32_e32 vcc, s97, v15
	v_ldexp_f32 v15, v17, v21
	v_cvt_f32_i32_e32 v17, s20
	v_cndmask_b32_e32 v14, v242, v14, vcc
	v_cmp_ngt_f32_e32 vcc, s96, v16
	v_div_scale_f32 v21, s[20:21], s95, s95, v17
	v_rcp_f32_e32 v22, v21
	v_cndmask_b32_e32 v15, 0, v15, vcc
	v_cmp_nlt_f32_e32 vcc, s97, v16
	s_nop 1
	v_cndmask_b32_e32 v15, v242, v15, vcc
	v_pk_add_f32 v[14:15], v[14:15], s[26:27] op_sel_hi:[1,0]
	s_nop 0
	v_pk_mul_f32 v[12:13], v[14:15], v[12:13]
	v_fma_f32 v14, -v21, v22, 1.0
	v_fmac_f32_e32 v22, v14, v22
	v_div_scale_f32 v14, vcc, v17, s95, v17
	v_mul_f32_e32 v15, v14, v22
	v_fma_f32 v16, -v21, v15, v14
	v_fmac_f32_e32 v15, v16, v22
	v_fma_f32 v14, -v21, v15, v14
	v_div_fmas_f32 v14, v14, v22, v15
	v_div_fixup_f32 v14, v14, s95, v17
	v_mul_f32_e64 v14, |v29|, v14
	v_mul_f32_e32 v15, 0x3fb8aa3b, v14
	v_fma_f32 v16, v14, s71, -v15
	v_rndne_f32_e32 v17, v15
	v_fmac_f32_e32 v16, 0x32a5705f, v14
	v_sub_f32_e32 v15, v15, v17
	v_add_f32_e32 v15, v15, v16
	v_cvt_f32_i32_e32 v16, s13
	v_exp_f32_e32 v15, v15
	v_cvt_i32_f32_e32 v17, v17
	v_add_f32_e64 v20, |v12|, v20
	v_div_scale_f32 v21, s[20:21], s95, s95, v16
	v_rcp_f32_e32 v22, v21
	v_ldexp_f32 v15, v15, v17
	v_add_f32_e64 v20, |v13|, v20
	s_mov_b64 s[20:21], 0
	v_fma_f32 v17, -v21, v22, 1.0
	v_fmac_f32_e32 v22, v17, v22
	v_div_scale_f32 v17, vcc, v16, s95, v16
	v_mul_f32_e32 v23, v17, v22
	v_fma_f32 v24, -v21, v23, v17
	v_fmac_f32_e32 v23, v24, v22
	v_fma_f32 v17, -v21, v23, v17
	v_div_fmas_f32 v17, v17, v22, v23
	v_div_fixup_f32 v16, v17, s95, v16
	v_mul_f32_e64 v16, |v29|, v16
	v_mul_f32_e32 v17, 0x3fb8aa3b, v16
	v_fma_f32 v21, v16, s71, -v17
	v_rndne_f32_e32 v22, v17
	v_fmac_f32_e32 v21, 0x32a5705f, v16
	v_sub_f32_e32 v17, v17, v22
	v_add_f32_e32 v17, v17, v21
	v_exp_f32_e32 v17, v17
	v_cvt_i32_f32_e32 v21, v22
	v_cmp_ngt_f32_e32 vcc, s96, v14
	s_nop 1
	v_cndmask_b32_e32 v15, 0, v15, vcc
	v_cmp_nlt_f32_e32 vcc, s97, v14
	s_nop 1
	v_cndmask_b32_e32 v14, v242, v15, vcc
	v_ldexp_f32 v15, v17, v21
	v_cmp_ngt_f32_e32 vcc, s96, v16
	s_nop 1
	v_cndmask_b32_e32 v15, 0, v15, vcc
	v_cmp_nlt_f32_e32 vcc, s97, v16
	s_nop 1
	v_cndmask_b32_e32 v15, v242, v15, vcc
	v_pk_add_f32 v[14:15], v[14:15], s[26:27] op_sel_hi:[1,0]
	s_and_b64 vcc, exec, s[18:19]
	v_pk_mul_f32 v[14:15], v[14:15], v[10:11]
	global_store_dwordx4 v[18:19], v[12:15], off offset:48
	v_add_f32_e64 v10, |v14|, v20
	v_add_f32_e64 v32, |v15|, v10
	s_cbranch_vccz .LBB0_281
	s_lshl_b32 s11, s11, 9
	s_lshl_b32 s10, s10, 11
	s_or_b32 s10, s11, s10
	v_add_u32_e32 v6, s10, v30
	v_ashrrev_i32_e32 v7, 31, v6
	s_add_i32 s15, s15, s5
	s_add_i32 s14, s14, s5
	v_lshl_add_u64 v[6:7], v[6:7], 2, s[8:9]
	s_cmpk_gt_i32 s15, 0xff
	global_store_dword v[6:7], v32, off
	s_cbranch_scc0 .LBB0_280
